# in-loop grid barrier: last-arriving XCD leader releases every XCC generation word directly, other leaders poll their own word (one hop fewer); ODIN epilogue row-stat prefetch
# speedup vs baseline: 1.0037x; 1.0037x over previous
.LBB0_1239:
	s_lshl_b32 s33, s33, 8
	s_add_i32 s33, s33, s36
	v_or_b32_e32 v156, s33, v160
	v_ashrrev_i32_e32 v157, 31, v156
	v_lshlrev_b64 v[158:159], 6, v[156:157]
	v_lshl_add_u64 v[158:159], s[72:73], 0, v[158:159]
	global_load_dwordx4 v[164:167], v[158:159], off offset:48
	global_load_dwordx4 v[168:171], v[158:159], off offset:32
	global_load_dwordx4 v[174:177], v[158:159], off offset:16
	global_load_dwordx4 v[178:181], v[158:159], off
	v_add_co_u32_e32 v196, vcc, 0x2000, v158
	s_nop 1
	v_addc_co_u32_e32 v197, vcc, 0, v159, vcc
	global_load_dword v195, v[158:159], off offset:1024
	global_load_dword v195, v[158:159], off offset:2048
	global_load_dword v195, v[158:159], off offset:3072
	global_load_dword v195, v[196:197], off
	global_load_dword v195, v[196:197], off offset:1024
	global_load_dword v195, v[196:197], off offset:2048
	global_load_dword v195, v[196:197], off offset:3072
	v_lshl_or_b32 v154, s44, 8, v162
	s_cmp_gt_i32 s44, 1
	s_cselect_b64 s[0:1], -1, 0
	s_ashr_i32 s44, s33, 4
	s_addk_i32 s44, 0x8000
	s_mov_b64 s[4:5], -1
	s_waitcnt vmcnt(0)
	v_add_f32_e32 v168, v168, v169
	v_add_f32_e32 v170, v170, v171
	v_mov_b32_e32 v158, v179
	v_mov_b32_e32 v159, v180
	v_mov_b32_e32 v179, v181
	v_pk_add_f32 v[158:159], v[158:159], v[178:179]
	v_mov_b32_e32 v178, v175
	v_mov_b32_e32 v179, v176
	v_mov_b32_e32 v175, v177
	v_pk_add_f32 v[174:175], v[178:179], v[174:175]
	v_pk_add_f32 v[158:159], v[158:159], v[158:159] op_sel:[0,1] op_sel_hi:[1,0]
	v_pk_add_f32 v[174:175], v[174:175], v[174:175] op_sel:[0,1] op_sel_hi:[1,0]
	v_mov_b32_e32 v159, v164
	v_mov_b32_e32 v175, v165
	v_mov_b32_e32 v169, v166
	v_mov_b32_e32 v171, v167
	v_pk_add_f32 v[158:159], v[158:159], v[174:175]
	v_pk_add_f32 v[164:165], v[168:169], v[170:171]
	s_nop 0
	v_pk_add_f32 v[158:159], v[158:159], v[164:165]
	s_nop 0
	v_add_f32_e32 v155, v158, v159
	v_fmamk_f32 v155, v155, 0x3a800000, v184
	v_cmp_gt_f32_e32 vcc, s80, v155
	v_mul_f32_e32 v158, 0x4b800000, v155
	s_nop 0
	v_cndmask_b32_e32 v155, v155, v158, vcc
	v_rsq_f32_e32 v155, v155
	s_nop 0
	v_mul_f32_e32 v158, 0x45800000, v155
	v_cndmask_b32_e32 v158, v155, v158, vcc
	v_pk_mul_f32 v[122:123], v[122:123], v[158:159] op_sel_hi:[1,0]
	v_pk_mul_f32 v[126:127], v[126:127], v[158:159] op_sel_hi:[1,0]
	v_pk_mul_f32 v[124:125], v[124:125], v[158:159] op_sel_hi:[1,0]
	v_pk_mul_f32 v[128:129], v[128:129], v[158:159] op_sel_hi:[1,0]
	v_lshlrev_b32_e32 v155, 6, v154
	s_and_b64 vcc, exec, s[0:1]
	v_and_b32_e32 v164, 0xffffdc00, v155
	v_cvt_pk_bf16_f32 v122, v122, v123
	v_cvt_pk_bf16_f32 v123, v124, v125
	v_cvt_pk_bf16_f32 v124, v126, v127
	v_cvt_pk_bf16_f32 v125, v128, v129
	s_cbranch_vccz .LBB0_1241
	v_add_u32_e32 v126, s44, v164
	v_ashrrev_i32_e32 v127, 31, v126
	v_lshlrev_b64 v[126:127], 9, v[126:127]
	v_lshl_add_u64 v[126:127], v[148:149], 0, v[126:127]
	global_store_dwordx4 v[126:127], v[122:125], off
	s_mov_b64 s[4:5], 0

.LBB0_1691:
	s_andn2_saveexec_b64 s[4:5], s[4:5]
	s_cbranch_execz .LBB0_1711
	v_mov_b32_e32 v9, v2
	s_mov_b64 s[4:5], exec
	buffer_wbl2 sc1
	s_waitcnt lgkmcnt(0)
	s_waitcnt vmcnt(0)
	v_mbcnt_lo_u32_b32 v2, s4, 0
	v_mbcnt_hi_u32_b32 v2, s5, v2
	v_cmp_eq_u32_e32 vcc, 0, v2
	s_and_saveexec_b64 s[6:7], vcc
	s_cbranch_execz .LBB0_1694
	s_bcnt1_i32_b64 s4, s[4:5]
	v_mov_b32_e32 v3, s4
	v_mov_b32_e32 v4, 0xd683000
	global_atomic_add v3, v4, v3, s[64:65] offset:1024 sc0
.LBB0_1694:
	s_or_b64 exec, exec, s[6:7]
	v_cvt_f32_u32_e32 v4, v0
	s_waitcnt vmcnt(0)
	v_readfirstlane_b32 s4, v3
	s_add_u32 s6, s64, 0xd683500
	s_addc_u32 s7, s65, 0
	v_rcp_iflag_f32_e32 v4, v4
	v_add_u32_e32 v2, s4, v2
	v_add_u32_e32 v5, 1, v2
	s_mov_b64 s[8:9], -1
	v_mul_f32_e32 v3, 0x4f7ffffe, v4
	v_cvt_u32_f32_e32 v3, v3
	v_sub_u32_e32 v4, 0, v0
	v_mul_lo_u32 v4, v4, v3
	v_mul_hi_u32 v4, v3, v4
	v_add_u32_e32 v3, v3, v4
	v_mul_hi_u32 v3, v2, v3
	v_mul_lo_u32 v4, v3, v0
	v_sub_u32_e32 v2, v2, v4
	v_add_u32_e32 v6, 1, v3
	v_cmp_ge_u32_e32 vcc, v2, v0
	v_sub_u32_e32 v4, v2, v0
	s_nop 0
	v_cndmask_b32_e32 v3, v3, v6, vcc
	v_cndmask_b32_e32 v2, v2, v4, vcc
	v_add_u32_e32 v4, 1, v3
	v_cmp_ge_u32_e32 vcc, v2, v0
	s_nop 1
	v_cndmask_b32_e32 v4, v3, v4, vcc
	v_mul_lo_u32 v2, v0, v4
	v_add_u32_e32 v0, v2, v0
	v_cmp_ne_u32_e32 vcc, v5, v0
	s_cbranch_vccnz .Lxb_lpoll
	v_mov_b32_e32 v4, 0xd682400
	global_atomic_add v4, v188, s[64:65]
	global_atomic_add v4, v188, s[64:65] offset:256
	global_atomic_add v4, v188, s[64:65] offset:512
	global_atomic_add v4, v188, s[64:65] offset:768
	global_atomic_add v4, v188, s[64:65] offset:1024
	global_atomic_add v4, v188, s[64:65] offset:1280
	global_atomic_add v4, v188, s[64:65] offset:1536
	global_atomic_add v4, v188, s[64:65] offset:1792
	global_atomic_add v4, v188, s[64:65] offset:2048
	global_atomic_add v4, v188, s[64:65] offset:2304
	global_atomic_add v4, v188, s[64:65] offset:2560
	global_atomic_add v4, v188, s[64:65] offset:2816
	global_atomic_add v4, v188, s[64:65] offset:3072
	global_atomic_add v4, v188, s[64:65] offset:3328
	global_atomic_add v4, v188, s[64:65] offset:3584
	global_atomic_add v4, v188, s[64:65] offset:3840
	s_branch .Lxb_lacq
.Lxb_lpoll:
	s_mov_b32 s22, 1
.Lxb_lloop:
	global_load_dword v0, v187, s[2:3] offset:1024 sc1
	s_waitcnt vmcnt(0)
	v_cmp_ne_u32_e32 vcc, v0, v9
	s_cbranch_vccnz .Lxb_lacq
	s_sleep 1
	s_add_i32 s22, s22, 1
	s_cmp_lt_u32 s22, 0x400000
	s_cbranch_scc1 .Lxb_lloop
.Lxb_lacq:
	s_waitcnt vmcnt(0)
	buffer_inv sc1
	s_waitcnt vmcnt(0)
